# tile index of the unit after next computed on the SALU in all four GEMM copies (no float-reciprocal division chain on the unit hand-over); on top of pass1 prefetch, pass2 hoist + gain reuse, peeled GE
# baseline (speedup 1.0000x reference)
;     __host__ __device__ bool next(int i, Unit& u) const {
;         const long L = (long)i * G + c; if (L >= nwg) return false;
;         int wgid = (int)L; { const int q = nwg / NXCD, r = nwg % NXCD, xcd = wgid % NXCD, off = wgid / NXCD; wgid = (xcd < r ? xcd * (q + 1) : r * (q + 1) + (xcd - r) * q) + off; }
;         const int nig = WGM * nN, gid = wgid / nig, fm = gid * WGM, gsz = (nM - fm) < WGM ? (nM - fm) : WGM;
;         u.pm = fm + ((wgid % nig) % gsz); u.pn = (wgid % nig) / gsz; u.idx = i; return true;
;     }
.LBB0_62:
	s_add_i32 s40, s40, 1
	s_mul_i32 s9, s40, s73
	s_mul_hi_u32 s11, s40, s72
	s_add_i32 s11, s11, s9
	s_mul_i32 s9, s40, s72
	s_add_u32 s12, s9, s84
	s_addc_u32 s13, s11, s85
	v_mov_b64_e32 v[0:1], s[90:91]
	v_cmp_ge_i64_e32 vcc, s[12:13], v[0:1]
	v_cmp_lt_i64_e64 s[42:43], s[12:13], v[0:1]
	s_cbranch_vccnz .LBB0_64
	s_and_b32 s8, s12, 7
	s_mul_i32 s8, s8, s26
	s_lshr_b32 s9, s12, 3
	s_add_i32 s8, s8, s9
	s_mul_hi_u32 s9, s8, 0x1745d18
	s_mul_i32 s10, s9, 0xb0
	s_sub_i32 s8, s8, s10
	s_lshl_b32 s10, s9, 3
	s_and_b32 s9, s8, 7
	s_add_i32 s10, s10, s9
	s_lshr_b32 s8, s8, 3
	s_mov_b32 s41, s40

;     __host__ __device__ bool next(int i, Unit& u) const {
;         const long L = (long)i * G + c; if (L >= nwg) return false;
;         int wgid = (int)L; { const int q = nwg / NXCD, r = nwg % NXCD, xcd = wgid % NXCD, off = wgid / NXCD; wgid = (xcd < r ? xcd * (q + 1) : r * (q + 1) + (xcd - r) * q) + off; }
;         const int nig = WGM * nN, gid = wgid / nig, fm = gid * WGM, gsz = (nM - fm) < WGM ? (nM - fm) : WGM;
;         u.pm = fm + ((wgid % nig) % gsz); u.pn = (wgid % nig) / gsz; u.idx = i; return true;
;     }
.LBB0_90:
	s_add_i32 s37, s37, 1
	s_mul_i32 s0, s37, s73
	s_mul_hi_u32 s1, s37, s72
	s_add_i32 s1, s1, s0
	s_mul_i32 s0, s37, s72
	s_add_u32 s16, s0, s84
	s_addc_u32 s17, s1, s85
	s_waitcnt lgkmcnt(0)
	v_mov_b64_e32 v[0:1], s[6:7]
	v_cmp_ge_i64_e32 vcc, s[16:17], v[0:1]
	v_cmp_lt_i64_e64 s[0:1], s[16:17], v[0:1]
	s_cbranch_vccnz .LBB0_92
	s_and_b32 s3, s16, 7
	s_mul_i32 s3, s3, s48
	s_lshr_b32 s17, s16, 3
	s_add_i32 s3, s3, s17
	s_lshr_b32 s17, s3, 5
	s_and_b32 s3, s3, 31
	s_lshl_b32 s49, s17, 3
	s_and_b32 s17, s3, 7
	s_add_i32 s49, s49, s17
	s_lshr_b32 s3, s3, 3

;     __host__ __device__ bool next(int i, Unit& u) const {
;         const long L = (long)i * G + c; if (L >= nwg) return false;
;         int wgid = (int)L; { const int q = nwg / NXCD, r = nwg % NXCD, xcd = wgid % NXCD, off = wgid / NXCD; wgid = (xcd < r ? xcd * (q + 1) : r * (q + 1) + (xcd - r) * q) + off; }
;         const int nig = WGM * nN, gid = wgid / nig, fm = gid * WGM, gsz = (nM - fm) < WGM ? (nM - fm) : WGM;
;         u.pm = fm + ((wgid % nig) % gsz); u.pn = (wgid % nig) / gsz; u.idx = i; return true;
;     }
.LBB0_249:
	s_add_i32 s37, s37, 1
	s_mul_i32 s7, s37, s73
	s_mul_hi_u32 s9, s37, s72
	s_add_i32 s9, s9, s7
	s_mul_i32 s7, s37, s72
	s_add_u32 s10, s7, s84
	s_addc_u32 s11, s9, s85
	v_mov_b64_e32 v[0:1], s[90:91]
	v_cmp_ge_i64_e32 vcc, s[10:11], v[0:1]
	v_cmp_lt_i64_e64 s[42:43], s[10:11], v[0:1]
	s_cbranch_vccnz .LBB0_251
	s_and_b32 s6, s10, 7
	s_mul_i32 s6, s6, s23
	s_lshr_b32 s7, s10, 3
	s_add_i32 s6, s6, s7
	s_mul_hi_u32 s7, s6, 0x2aaaaab
	s_mul_i32 s8, s7, 0x60
	s_sub_i32 s6, s6, s8
	s_lshl_b32 s8, s7, 3
	s_and_b32 s7, s6, 7
	s_add_i32 s8, s8, s7
	s_lshr_b32 s6, s6, 3
	s_mov_b32 s38, s37

;     __host__ __device__ bool next(int i, Unit& u) const {
;         const long L = (long)i * G + c; if (L >= nwg) return false;
;         int wgid = (int)L; { const int q = nwg / NXCD, r = nwg % NXCD, xcd = wgid % NXCD, off = wgid / NXCD; wgid = (xcd < r ? xcd * (q + 1) : r * (q + 1) + (xcd - r) * q) + off; }
;         const int nig = WGM * nN, gid = wgid / nig, fm = gid * WGM, gsz = (nM - fm) < WGM ? (nM - fm) : WGM;
;         u.pm = fm + ((wgid % nig) % gsz); u.pn = (wgid % nig) / gsz; u.idx = i; return true;
;     }
.LBB0_470:
	s_add_i32 s22, s22, 1
	s_mul_i32 s5, s22, s73
	s_mul_hi_u32 s10, s22, s72
	s_add_i32 s5, s10, s5
	s_mul_i32 s10, s22, s72
	s_add_u32 s10, s10, s84
	s_addc_u32 s11, s5, s85
	v_mov_b64_e32 v[0:1], s[90:91]
	v_cmp_ge_i64_e32 vcc, s[10:11], v[0:1]
	v_cmp_lt_i64_e64 s[60:61], s[10:11], v[0:1]
	s_cbranch_vccnz .LBB0_472
	s_and_b32 s5, s10, 7
	s_lshl_b32 s11, s12, 1
	s_mul_i32 s5, s5, s11
	s_lshr_b32 s11, s10, 3
	s_add_i32 s5, s5, s11
	s_lshr_b32 s11, s5, 7
	s_and_b32 s5, s5, 0x7f
	s_lshl_b32 s54, s11, 3
	s_and_b32 s11, s5, 7
	s_add_i32 s54, s54, s11
	s_lshr_b32 s52, s5, 3
	s_mov_b32 s23, s22
